# P4 spectrum multiply: the 16 filter-spectrum loads per loop iteration issued together with one wait instead of four waited groups
# speedup vs baseline: 1.0299x; 1.0006x over previous
.LBB0_476:
	v_ashrrev_i32_e32 v7, 31, v2
	v_mov_b32_e32 v6, v2
	v_ashrrev_i32_e32 v5, 31, v3
	v_mov_b32_e32 v4, v3
	v_lshl_add_u64 v[6:7], v[6:7], 3, s[2:3]
	v_lshl_add_u64 v[4:5], v[4:5], 3, s[2:3]
	v_add_co_u32_e32 v172, vcc, s39, v6
	s_nop 1
	v_addc_co_u32_e32 v173, vcc, 0, v7, vcc
	v_add_co_u32_e32 v174, vcc, s39, v4
	s_nop 1
	v_addc_co_u32_e32 v175, vcc, 0, v5, vcc
	v_add_co_u32_e32 v176, vcc, s37, v6
	s_nop 1
	v_addc_co_u32_e32 v177, vcc, 0, v7, vcc
	v_add_co_u32_e32 v178, vcc, s37, v4
	s_nop 1
	v_addc_co_u32_e32 v179, vcc, 0, v5, vcc
	v_add_co_u32_e32 v180, vcc, s48, v6
	s_nop 1
	v_addc_co_u32_e32 v181, vcc, 0, v7, vcc
	v_add_co_u32_e32 v182, vcc, s48, v4
	s_nop 1
	v_addc_co_u32_e32 v183, vcc, 0, v5, vcc
	v_add_co_u32_e32 v184, vcc, s28, v6
	s_nop 1
	v_addc_co_u32_e32 v185, vcc, 0, v7, vcc
	v_add_co_u32_e32 v186, vcc, s28, v4
	s_nop 1
	v_addc_co_u32_e32 v187, vcc, 0, v5, vcc
	global_load_dwordx2 v[188:189], v[6:7], off
	global_load_dwordx2 v[190:191], v[4:5], off
	global_load_dwordx2 v[192:193], v[172:173], off offset:-4096
	global_load_dwordx2 v[194:195], v[174:175], off offset:-4096
	global_load_dwordx2 v[196:197], v[172:173], off
	global_load_dwordx2 v[198:199], v[174:175], off
	global_load_dwordx2 v[200:201], v[176:177], off offset:-4096
	global_load_dwordx2 v[202:203], v[178:179], off offset:-4096
	global_load_dwordx2 v[204:205], v[176:177], off
	global_load_dwordx2 v[206:207], v[178:179], off
	global_load_dwordx2 v[208:209], v[180:181], off offset:-4096
	global_load_dwordx2 v[210:211], v[182:183], off offset:-4096
	global_load_dwordx2 v[212:213], v[180:181], off
	global_load_dwordx2 v[214:215], v[182:183], off
	global_load_dwordx2 v[216:217], v[184:185], off
	global_load_dwordx2 v[218:219], v[186:187], off
	v_add_u32_e32 v56, -2, v56
	v_add_u32_e32 v3, 0x2000, v3
	v_add_u32_e32 v2, 0x2000, v2
	v_cmp_eq_u32_e32 vcc, 0, v56
	s_or_b64 s[8:9], vcc, s[8:9]
	s_waitcnt vmcnt(0)
	v_mov_b32_e32 v34, v188
	v_mov_b32_e32 v35, v190
	v_mov_b32_e32 v32, v189
	v_mov_b32_e32 v33, v191
	v_mov_b32_e32 v30, v192
	v_mov_b32_e32 v31, v194
	v_mov_b32_e32 v28, v193
	v_mov_b32_e32 v29, v195
	v_mov_b32_e32 v26, v196
	v_mov_b32_e32 v27, v198
	v_mov_b32_e32 v24, v197
	v_mov_b32_e32 v25, v199
	v_mov_b32_e32 v22, v200
	v_mov_b32_e32 v23, v202
	v_mov_b32_e32 v20, v201
	v_mov_b32_e32 v21, v203
	v_mov_b32_e32 v18, v204
	v_mov_b32_e32 v19, v206
	v_mov_b32_e32 v16, v205
	v_mov_b32_e32 v17, v207
	v_mov_b32_e32 v14, v208
	v_mov_b32_e32 v15, v210
	v_mov_b32_e32 v12, v209
	v_mov_b32_e32 v13, v211
	v_mov_b32_e32 v10, v212
	v_mov_b32_e32 v11, v214
	v_mov_b32_e32 v8, v213
	v_mov_b32_e32 v9, v215
	v_mov_b32_e32 v6, v216
	v_mov_b32_e32 v7, v218
	v_mov_b32_e32 v4, v217
	v_mov_b32_e32 v5, v219
	ds_read2st64_b64 v[58:61], v53 offset1:8
	ds_read2st64_b64 v[62:65], v53 offset0:64 offset1:72
	s_waitcnt lgkmcnt(1)
	v_mov_b32_e32 v66, v58
	s_waitcnt lgkmcnt(0)
	v_mov_b32_e32 v67, v62
	v_mov_b32_e32 v62, v59
	v_pk_mul_f32 v[58:59], v[62:63], v[32:33]
	v_pk_mul_f32 v[32:33], v[66:67], v[32:33]
	v_pk_fma_f32 v[58:59], v[66:67], v[34:35], v[58:59] neg_lo:[0,0,1] neg_hi:[0,0,1]
	v_pk_fma_f32 v[32:33], v[62:63], v[34:35], v[32:33]
	v_mov_b32_e32 v34, v58
	v_mov_b32_e32 v35, v32
	v_mov_b32_e32 v32, v59
	v_mov_b32_e32 v58, v60
	v_mov_b32_e32 v59, v64
	v_mov_b32_e32 v64, v61
	v_pk_mul_f32 v[60:61], v[64:65], v[28:29]
	v_pk_mul_f32 v[28:29], v[58:59], v[28:29]
	v_pk_fma_f32 v[60:61], v[58:59], v[30:31], v[60:61] neg_lo:[0,0,1] neg_hi:[0,0,1]
	v_pk_fma_f32 v[28:29], v[64:65], v[30:31], v[28:29]
	v_mov_b32_e32 v30, v60
	v_mov_b32_e32 v31, v28
	v_mov_b32_e32 v28, v61
	ds_write2st64_b64 v53, v[34:35], v[30:31] offset1:8
	ds_write2st64_b64 v53, v[32:33], v[28:29] offset0:64 offset1:72
	ds_read2st64_b64 v[28:31], v53 offset0:16 offset1:24
	ds_read2st64_b64 v[32:35], v53 offset0:80 offset1:88
	s_waitcnt lgkmcnt(1)
	v_mov_b32_e32 v58, v28
	s_waitcnt lgkmcnt(0)
	v_mov_b32_e32 v59, v32
	v_mov_b32_e32 v32, v29
	v_pk_mul_f32 v[28:29], v[32:33], v[24:25]
	v_pk_mul_f32 v[24:25], v[58:59], v[24:25]
	v_pk_fma_f32 v[28:29], v[58:59], v[26:27], v[28:29] neg_lo:[0,0,1] neg_hi:[0,0,1]
	v_pk_fma_f32 v[24:25], v[32:33], v[26:27], v[24:25]
	v_mov_b32_e32 v26, v28
	v_mov_b32_e32 v27, v24
	v_mov_b32_e32 v24, v29
	v_mov_b32_e32 v28, v30
	v_mov_b32_e32 v29, v34
	v_mov_b32_e32 v34, v31
	v_pk_mul_f32 v[30:31], v[34:35], v[20:21]
	v_pk_mul_f32 v[20:21], v[28:29], v[20:21]
	v_pk_fma_f32 v[30:31], v[28:29], v[22:23], v[30:31] neg_lo:[0,0,1] neg_hi:[0,0,1]
	v_pk_fma_f32 v[20:21], v[34:35], v[22:23], v[20:21]
	v_mov_b32_e32 v22, v30
	v_mov_b32_e32 v23, v20
	v_mov_b32_e32 v20, v31
	ds_write2st64_b64 v53, v[26:27], v[22:23] offset0:16 offset1:24
	ds_write2st64_b64 v53, v[24:25], v[20:21] offset0:80 offset1:88
	ds_read2st64_b64 v[20:23], v53 offset0:32 offset1:40
	ds_read2st64_b64 v[24:27], v53 offset0:96 offset1:104
	s_waitcnt lgkmcnt(1)
	v_mov_b32_e32 v28, v20
	s_waitcnt lgkmcnt(0)
	v_mov_b32_e32 v29, v24
	v_mov_b32_e32 v24, v21
	v_pk_mul_f32 v[20:21], v[24:25], v[16:17]
	v_pk_mul_f32 v[16:17], v[28:29], v[16:17]
	v_pk_fma_f32 v[20:21], v[28:29], v[18:19], v[20:21] neg_lo:[0,0,1] neg_hi:[0,0,1]
	v_pk_fma_f32 v[16:17], v[24:25], v[18:19], v[16:17]
	v_mov_b32_e32 v18, v20
	v_mov_b32_e32 v19, v16
	v_mov_b32_e32 v16, v21
	v_mov_b32_e32 v20, v22
	v_mov_b32_e32 v21, v26
	v_mov_b32_e32 v26, v23
	v_pk_mul_f32 v[22:23], v[26:27], v[12:13]
	v_pk_mul_f32 v[12:13], v[20:21], v[12:13]
	v_pk_fma_f32 v[22:23], v[20:21], v[14:15], v[22:23] neg_lo:[0,0,1] neg_hi:[0,0,1]
	v_pk_fma_f32 v[12:13], v[26:27], v[14:15], v[12:13]
	v_mov_b32_e32 v14, v22
	v_mov_b32_e32 v15, v12
	v_mov_b32_e32 v12, v23
	ds_write2st64_b64 v53, v[18:19], v[14:15] offset0:32 offset1:40
	ds_write2st64_b64 v53, v[16:17], v[12:13] offset0:96 offset1:104
	ds_read2st64_b64 v[12:15], v53 offset0:48 offset1:56
	ds_read2st64_b64 v[16:19], v53 offset0:112 offset1:120
	s_waitcnt lgkmcnt(1)
	v_mov_b32_e32 v20, v12
	s_waitcnt lgkmcnt(0)
	v_mov_b32_e32 v21, v16
	v_mov_b32_e32 v16, v13
	v_pk_mul_f32 v[12:13], v[16:17], v[8:9]
	v_pk_mul_f32 v[8:9], v[20:21], v[8:9]
	v_pk_fma_f32 v[12:13], v[20:21], v[10:11], v[12:13] neg_lo:[0,0,1] neg_hi:[0,0,1]
	v_pk_fma_f32 v[8:9], v[16:17], v[10:11], v[8:9]
	v_mov_b32_e32 v10, v12
	v_mov_b32_e32 v11, v8
	v_mov_b32_e32 v8, v13
	v_mov_b32_e32 v12, v14
	v_mov_b32_e32 v13, v18
	v_mov_b32_e32 v18, v15
	v_pk_mul_f32 v[14:15], v[18:19], v[4:5]
	v_pk_mul_f32 v[4:5], v[12:13], v[4:5]
	v_pk_fma_f32 v[14:15], v[12:13], v[6:7], v[14:15] neg_lo:[0,0,1] neg_hi:[0,0,1]
	v_pk_fma_f32 v[4:5], v[18:19], v[6:7], v[4:5]
	v_mov_b32_e32 v6, v14
	v_mov_b32_e32 v7, v4
	v_mov_b32_e32 v4, v15
	ds_write2st64_b64 v53, v[10:11], v[6:7] offset0:48 offset1:56
	ds_write2st64_b64 v53, v[8:9], v[4:5] offset0:112 offset1:120
	v_add_u32_e32 v53, 0x10000, v53
	s_andn2_b64 exec, exec, s[8:9]
	s_cbranch_execnz .LBB0_476
	s_or_b64 exec, exec, s[8:9]
	v_cmp_ne_u32_e32 vcc, v54, v55
	v_lshl_add_u32 v4, v55, 12, v0
	s_orn2_b64 s[2:3], vcc, exec
